# P1 in-proj GEMM epilogue: the 16 output stores per wave carry the nt (streaming) cache policy
# speedup vs baseline: 1.0141x; 1.0114x over previous
; __device__ __forceinline__ unsigned cvt_pk_bf16(float lo, float hi) { unsigned r; asm volatile("v_cvt_pk_bf16_f32 %0, %1, %2" : "=v"(r) : "v"(lo), "v"(hi)); return r; }
; __device__ __forceinline__ float silu_f(float v) { return v * __builtin_amdgcn_rcpf(1.0f + __builtin_amdgcn_exp2f(-1.4426950408889634f * v)); }
;     __device__ __forceinline__ void operator()(const f32x4 (&acc)[2][2][4][2], const Unit& u, int wr, int wc, int fr, int fq) const {
;         const int g = u.pn >> 2, cin = (u.pn & 3) * BM;
;         bf16_t* base = g == 0 ? AO : g == 1 ? VA : g == 2 ? ZA : g == 3 ? AO + 1024 : g == 4 ? KB : g == 5 ? VB : ZB;
;         const int ldc = (g == 0 || g == 3) ? 2048 : 1024;
;         const bool act = (g == 2 || g == 6);
;         const int row0 = u.pm * BM + wr * 64 + fr, col0 = cin + wc * 32 + 8 * fq;
; #pragma unroll
;         for (int ai = 0; ai < 2; ++ai)
; #pragma unroll
;             for (int m = 0; m < 4; ++m) { bf16_t* rowp = base + (size_t)(row0 + ai * HALF + m * 16) * ldc + col0;
; #pragma unroll
;                 for (int bj = 0; bj < 2; ++bj) { f32x4 v0 = acc[ai][bj][m][0], v1 = acc[ai][bj][m][1];
;                     if (act) {
; #pragma unroll
;                         for (int e = 0; e < 4; ++e) { v0[e] = silu_f(v0[e]); v1[e] = silu_f(v1[e]); } }
;                     u32x4 w; w.x = cvt_pk_bf16(v0[0], v0[1]); w.y = cvt_pk_bf16(v0[2], v0[3]); w.z = cvt_pk_bf16(v1[0], v1[1]); w.w = cvt_pk_bf16(v1[2], v1[3]);
;                     *(u32x4*)(rowp + bj * HALF) = w; } }
.LBB0_127:
	s_lshl_b32 s17, s64, 8
	s_and_b32 s17, s17, 0x300
	s_cmp_eq_u32 s5, 3
	s_cselect_b64 s[72:73], -1, 0
	s_or_b64 s[66:67], s[66:67], s[72:73]
	v_lshl_add_u32 v148, s4, 8, v1
	v_or_b32_e32 v138, s17, v155
	s_and_b64 s[4:5], s[66:67], exec
	s_cselect_b32 s17, 11, 10
	v_lshlrev_b32_e32 v138, 1, v138
	v_ashrrev_i32_e32 v149, 31, v148
	v_lshl_add_u64 v[150:151], s[68:69], 0, v[138:139]
	v_lshlrev_b64 v[152:153], s17, v[148:149]
	v_cvt_pk_bf16_f32 v126, v126, v127
	v_cvt_pk_bf16_f32 v127, v128, v129
	v_cvt_pk_bf16_f32 v128, v122, v123
	v_cndmask_b32_e64 v122, 0, 1, s[70:71]
	v_lshl_add_u64 v[152:153], v[152:153], 1, v[150:151]
	v_cmp_ne_u32_e64 s[4:5], 1, v122
	s_andn2_b64 vcc, exec, s[70:71]
	v_cvt_pk_bf16_f32 v129, v124, v125
	global_store_dwordx4 v[152:153], v[126:129], off nt
	s_cbranch_vccnz .LBB0_129
	v_mul_f32_e32 v123, 0xbfb8aa3b, v114
	v_mul_f32_e32 v124, 0xbfb8aa3b, v119
	v_exp_f32_e32 v123, v123
	v_exp_f32_e32 v125, v124
	v_mul_f32_e32 v127, 0xbfb8aa3b, v116
	v_mul_f32_e32 v128, 0xbfb8aa3b, v121
	v_add_f32_e32 v123, 1.0, v123
	v_mul_f32_e32 v122, 0xbfb8aa3b, v118
	v_rcp_f32_e32 v124, v123
	v_add_f32_e32 v123, 1.0, v125
	v_mul_f32_e32 v125, 0xbfb8aa3b, v115
	v_mul_f32_e32 v126, 0xbfb8aa3b, v120
	v_exp_f32_e32 v127, v127
	v_exp_f32_e32 v129, v128
	v_mul_f32_e32 v128, 0xbfb8aa3b, v117
	v_exp_f32_e32 v122, v122
	v_exp_f32_e32 v125, v125
	v_exp_f32_e32 v126, v126
	v_exp_f32_e32 v138, v128
	v_add_f32_e32 v127, 1.0, v127
	v_add_f32_e32 v122, 1.0, v122
	v_add_f32_e32 v125, 1.0, v125
	v_add_f32_e32 v126, 1.0, v126
	v_rcp_f32_e32 v128, v127
	v_add_f32_e32 v127, 1.0, v129
	v_add_f32_e32 v129, 1.0, v138
	v_rcp_f32_e32 v122, v122
	v_rcp_f32_e32 v123, v123
	v_rcp_f32_e32 v126, v126
	v_rcp_f32_e32 v127, v127
	v_rcp_f32_e32 v129, v129
	v_rcp_f32_e32 v125, v125
	v_pk_mul_f32 v[118:119], v[118:119], v[122:123]
	v_pk_mul_f32 v[120:121], v[120:121], v[126:127]
	v_pk_mul_f32 v[116:117], v[116:117], v[128:129]
	v_pk_mul_f32 v[114:115], v[114:115], v[124:125]
.LBB0_129:
	s_and_b64 vcc, exec, s[4:5]
	v_cvt_pk_bf16_f32 v118, v118, v119
	v_cvt_pk_bf16_f32 v119, v120, v121
	v_cvt_pk_bf16_f32 v120, v114, v115
	v_cvt_pk_bf16_f32 v121, v116, v117
	global_store_dwordx4 v[152:153], v[118:121], off offset:256 nt
	s_cbranch_vccnz .LBB0_131
	v_mul_f32_e32 v115, 0xbfb8aa3b, v106
	v_mul_f32_e32 v116, 0xbfb8aa3b, v111
	v_exp_f32_e32 v115, v115
	v_exp_f32_e32 v117, v116
	v_mul_f32_e32 v119, 0xbfb8aa3b, v108
	v_mul_f32_e32 v120, 0xbfb8aa3b, v113
	v_add_f32_e32 v115, 1.0, v115
	v_mul_f32_e32 v114, 0xbfb8aa3b, v110
	v_rcp_f32_e32 v116, v115
	v_add_f32_e32 v115, 1.0, v117
	v_mul_f32_e32 v117, 0xbfb8aa3b, v107
	v_mul_f32_e32 v118, 0xbfb8aa3b, v112
	v_exp_f32_e32 v119, v119
	v_exp_f32_e32 v121, v120
	v_mul_f32_e32 v120, 0xbfb8aa3b, v109
	v_exp_f32_e32 v114, v114
	v_exp_f32_e32 v117, v117
	v_exp_f32_e32 v118, v118
	v_exp_f32_e32 v122, v120
	v_add_f32_e32 v119, 1.0, v119
	v_add_f32_e32 v114, 1.0, v114
	v_add_f32_e32 v117, 1.0, v117
	v_add_f32_e32 v118, 1.0, v118
	v_rcp_f32_e32 v120, v119
	v_add_f32_e32 v119, 1.0, v121
	v_add_f32_e32 v121, 1.0, v122
	v_rcp_f32_e32 v114, v114
	v_rcp_f32_e32 v115, v115
	v_rcp_f32_e32 v118, v118
	v_rcp_f32_e32 v119, v119
	v_rcp_f32_e32 v121, v121
	v_rcp_f32_e32 v117, v117
	v_pk_mul_f32 v[110:111], v[110:111], v[114:115]
	v_pk_mul_f32 v[112:113], v[112:113], v[118:119]
	v_pk_mul_f32 v[108:109], v[108:109], v[120:121]
	v_pk_mul_f32 v[106:107], v[106:107], v[116:117]
.LBB0_131:
	v_or_b32_e32 v114, 16, v148
	v_ashrrev_i32_e32 v115, 31, v114
	v_lshlrev_b64 v[114:115], s17, v[114:115]
	v_lshl_add_u64 v[114:115], v[114:115], 1, v[150:151]
	s_and_b64 vcc, exec, s[4:5]
	v_cvt_pk_bf16_f32 v110, v110, v111
	v_cvt_pk_bf16_f32 v111, v112, v113
	v_cvt_pk_bf16_f32 v112, v106, v107
	v_cvt_pk_bf16_f32 v113, v108, v109
	global_store_dwordx4 v[114:115], v[110:113], off nt
	s_cbranch_vccnz .LBB0_133
	v_mul_f32_e32 v107, 0xbfb8aa3b, v98
	v_mul_f32_e32 v108, 0xbfb8aa3b, v103
	v_exp_f32_e32 v107, v107
	v_exp_f32_e32 v109, v108
	v_mul_f32_e32 v111, 0xbfb8aa3b, v100
	v_mul_f32_e32 v112, 0xbfb8aa3b, v105
	v_add_f32_e32 v107, 1.0, v107
	v_mul_f32_e32 v106, 0xbfb8aa3b, v102
	v_rcp_f32_e32 v108, v107
	v_add_f32_e32 v107, 1.0, v109
	v_mul_f32_e32 v109, 0xbfb8aa3b, v99
	v_mul_f32_e32 v110, 0xbfb8aa3b, v104
	v_exp_f32_e32 v111, v111
	v_exp_f32_e32 v113, v112
	v_mul_f32_e32 v112, 0xbfb8aa3b, v101
	v_exp_f32_e32 v106, v106
	v_exp_f32_e32 v109, v109
	v_exp_f32_e32 v110, v110
	v_exp_f32_e32 v116, v112
	v_add_f32_e32 v111, 1.0, v111
	v_add_f32_e32 v106, 1.0, v106
	v_add_f32_e32 v109, 1.0, v109
	v_add_f32_e32 v110, 1.0, v110
	v_rcp_f32_e32 v112, v111
	v_add_f32_e32 v111, 1.0, v113
	v_add_f32_e32 v113, 1.0, v116
	v_rcp_f32_e32 v106, v106
	v_rcp_f32_e32 v107, v107
	v_rcp_f32_e32 v110, v110
	v_rcp_f32_e32 v111, v111
	v_rcp_f32_e32 v113, v113
	v_rcp_f32_e32 v109, v109
	v_pk_mul_f32 v[102:103], v[102:103], v[106:107]
	v_pk_mul_f32 v[104:105], v[104:105], v[110:111]
	v_pk_mul_f32 v[100:101], v[100:101], v[112:113]
	v_pk_mul_f32 v[98:99], v[98:99], v[108:109]
; __device__ __forceinline__ unsigned cvt_pk_bf16(float lo, float hi) { unsigned r; asm volatile("v_cvt_pk_bf16_f32 %0, %1, %2" : "=v"(r) : "v"(lo), "v"(hi)); return r; }
; __device__ __forceinline__ float silu_f(float v) { return v * __builtin_amdgcn_rcpf(1.0f + __builtin_amdgcn_exp2f(-1.4426950408889634f * v)); }
;     __device__ __forceinline__ void operator()(const f32x4 (&acc)[2][2][4][2], const Unit& u, int wr, int wc, int fr, int fq) const {
;     ...
;             for (int m = 0; m < 4; ++m) { bf16_t* rowp = base + (size_t)(row0 + ai * HALF + m * 16) * ldc + col0;
; #pragma unroll
;                 for (int bj = 0; bj < 2; ++bj) { f32x4 v0 = acc[ai][bj][m][0], v1 = acc[ai][bj][m][1];
;                     if (act) {
; #pragma unroll
;                         for (int e = 0; e < 4; ++e) { v0[e] = silu_f(v0[e]); v1[e] = silu_f(v1[e]); } }
;                     u32x4 w; w.x = cvt_pk_bf16(v0[0], v0[1]); w.y = cvt_pk_bf16(v0[2], v0[3]); w.z = cvt_pk_bf16(v1[0], v1[1]); w.w = cvt_pk_bf16(v1[2], v1[3]);
;                     *(u32x4*)(rowp + bj * HALF) = w; } }
.LBB0_133:
	s_and_b64 vcc, exec, s[4:5]
	v_cvt_pk_bf16_f32 v102, v102, v103
	v_cvt_pk_bf16_f32 v103, v104, v105
	v_cvt_pk_bf16_f32 v104, v98, v99
	v_cvt_pk_bf16_f32 v105, v100, v101
	global_store_dwordx4 v[114:115], v[102:105], off offset:256 nt
	s_cbranch_vccnz .LBB0_135
	v_mul_f32_e32 v99, 0xbfb8aa3b, v90
	v_mul_f32_e32 v100, 0xbfb8aa3b, v95
	v_exp_f32_e32 v99, v99
	v_exp_f32_e32 v101, v100
	v_mul_f32_e32 v103, 0xbfb8aa3b, v92
	v_mul_f32_e32 v104, 0xbfb8aa3b, v97
	v_add_f32_e32 v99, 1.0, v99
	v_mul_f32_e32 v98, 0xbfb8aa3b, v94
	v_rcp_f32_e32 v100, v99
	v_add_f32_e32 v99, 1.0, v101
	v_mul_f32_e32 v101, 0xbfb8aa3b, v91
	v_mul_f32_e32 v102, 0xbfb8aa3b, v96
	v_exp_f32_e32 v103, v103
	v_exp_f32_e32 v105, v104
	v_mul_f32_e32 v104, 0xbfb8aa3b, v93
	v_exp_f32_e32 v98, v98
	v_exp_f32_e32 v101, v101
	v_exp_f32_e32 v102, v102
	v_exp_f32_e32 v106, v104
	v_add_f32_e32 v103, 1.0, v103
	v_add_f32_e32 v98, 1.0, v98
	v_add_f32_e32 v101, 1.0, v101
	v_add_f32_e32 v102, 1.0, v102
	v_rcp_f32_e32 v104, v103
	v_add_f32_e32 v103, 1.0, v105
	v_add_f32_e32 v105, 1.0, v106
	v_rcp_f32_e32 v98, v98
	v_rcp_f32_e32 v99, v99
	v_rcp_f32_e32 v102, v102
	v_rcp_f32_e32 v103, v103
	v_rcp_f32_e32 v105, v105
	v_rcp_f32_e32 v101, v101
	v_pk_mul_f32 v[94:95], v[94:95], v[98:99]
	v_pk_mul_f32 v[96:97], v[96:97], v[102:103]
	v_pk_mul_f32 v[92:93], v[92:93], v[104:105]
	v_pk_mul_f32 v[90:91], v[90:91], v[100:101]
.LBB0_135:
	v_or_b32_e32 v98, 32, v148
	v_ashrrev_i32_e32 v99, 31, v98
	v_lshlrev_b64 v[98:99], s17, v[98:99]
	v_lshl_add_u64 v[98:99], v[98:99], 1, v[150:151]
	s_and_b64 vcc, exec, s[4:5]
	v_cvt_pk_bf16_f32 v94, v94, v95
	v_cvt_pk_bf16_f32 v95, v96, v97
	v_cvt_pk_bf16_f32 v96, v90, v91
	v_cvt_pk_bf16_f32 v97, v92, v93
	global_store_dwordx4 v[98:99], v[94:97], off nt
	s_cbranch_vccnz .LBB0_137
	v_mul_f32_e32 v91, 0xbfb8aa3b, v82
	v_mul_f32_e32 v92, 0xbfb8aa3b, v87
	v_exp_f32_e32 v91, v91
	v_exp_f32_e32 v93, v92
	v_mul_f32_e32 v95, 0xbfb8aa3b, v84
	v_mul_f32_e32 v96, 0xbfb8aa3b, v89
	v_add_f32_e32 v91, 1.0, v91
	v_mul_f32_e32 v90, 0xbfb8aa3b, v86
	v_rcp_f32_e32 v92, v91
	v_add_f32_e32 v91, 1.0, v93
	v_mul_f32_e32 v93, 0xbfb8aa3b, v83
	v_mul_f32_e32 v94, 0xbfb8aa3b, v88
	v_exp_f32_e32 v95, v95
	v_exp_f32_e32 v97, v96
	v_mul_f32_e32 v96, 0xbfb8aa3b, v85
	v_exp_f32_e32 v90, v90
	v_exp_f32_e32 v93, v93
	v_exp_f32_e32 v94, v94
	v_exp_f32_e32 v100, v96
	v_add_f32_e32 v95, 1.0, v95
	v_add_f32_e32 v90, 1.0, v90
	v_add_f32_e32 v93, 1.0, v93
	v_add_f32_e32 v94, 1.0, v94
	v_rcp_f32_e32 v96, v95
	v_add_f32_e32 v95, 1.0, v97
	v_add_f32_e32 v97, 1.0, v100
	v_rcp_f32_e32 v90, v90
	v_rcp_f32_e32 v91, v91
	v_rcp_f32_e32 v94, v94
	v_rcp_f32_e32 v95, v95
	v_rcp_f32_e32 v97, v97
	v_rcp_f32_e32 v93, v93
	v_pk_mul_f32 v[86:87], v[86:87], v[90:91]
	v_pk_mul_f32 v[88:89], v[88:89], v[94:95]
	v_pk_mul_f32 v[84:85], v[84:85], v[96:97]
	v_pk_mul_f32 v[82:83], v[82:83], v[92:93]
.LBB0_137:
	s_and_b64 vcc, exec, s[4:5]
	v_cvt_pk_bf16_f32 v86, v86, v87
	v_cvt_pk_bf16_f32 v87, v88, v89
	v_cvt_pk_bf16_f32 v88, v82, v83
	v_cvt_pk_bf16_f32 v89, v84, v85
	global_store_dwordx4 v[98:99], v[86:89], off offset:256 nt
	s_cbranch_vccnz .LBB0_139
	v_mul_f32_e32 v83, 0xbfb8aa3b, v74
	v_mul_f32_e32 v84, 0xbfb8aa3b, v79
	v_exp_f32_e32 v83, v83
	v_exp_f32_e32 v85, v84
	v_mul_f32_e32 v87, 0xbfb8aa3b, v76
	v_mul_f32_e32 v88, 0xbfb8aa3b, v81
	v_add_f32_e32 v83, 1.0, v83
	v_mul_f32_e32 v82, 0xbfb8aa3b, v78
	v_rcp_f32_e32 v84, v83
	v_add_f32_e32 v83, 1.0, v85
	v_mul_f32_e32 v85, 0xbfb8aa3b, v75
	v_mul_f32_e32 v86, 0xbfb8aa3b, v80
	v_exp_f32_e32 v87, v87
	v_exp_f32_e32 v89, v88
	v_mul_f32_e32 v88, 0xbfb8aa3b, v77
	v_exp_f32_e32 v82, v82
	v_exp_f32_e32 v85, v85
	v_exp_f32_e32 v86, v86
	v_exp_f32_e32 v90, v88
	v_add_f32_e32 v87, 1.0, v87
	v_add_f32_e32 v82, 1.0, v82
	v_add_f32_e32 v85, 1.0, v85
	v_add_f32_e32 v86, 1.0, v86
	v_rcp_f32_e32 v88, v87
	v_add_f32_e32 v87, 1.0, v89
	v_add_f32_e32 v89, 1.0, v90
	v_rcp_f32_e32 v82, v82
	v_rcp_f32_e32 v83, v83
	v_rcp_f32_e32 v86, v86
	v_rcp_f32_e32 v87, v87
	v_rcp_f32_e32 v89, v89
	v_rcp_f32_e32 v85, v85
	v_pk_mul_f32 v[78:79], v[78:79], v[82:83]
	v_pk_mul_f32 v[80:81], v[80:81], v[86:87]
	v_pk_mul_f32 v[76:77], v[76:77], v[88:89]
	v_pk_mul_f32 v[74:75], v[74:75], v[84:85]
.LBB0_139:
	v_or_b32_e32 v82, 48, v148
	v_ashrrev_i32_e32 v83, 31, v82
	v_lshlrev_b64 v[82:83], s17, v[82:83]
	v_lshl_add_u64 v[82:83], v[82:83], 1, v[150:151]
	s_and_b64 vcc, exec, s[4:5]
	v_cvt_pk_bf16_f32 v78, v78, v79
	v_cvt_pk_bf16_f32 v79, v80, v81
	v_cvt_pk_bf16_f32 v80, v74, v75
	v_cvt_pk_bf16_f32 v81, v76, v77
	global_store_dwordx4 v[82:83], v[78:81], off nt
	s_cbranch_vccnz .LBB0_141
	v_mul_f32_e32 v75, 0xbfb8aa3b, v66
	v_mul_f32_e32 v76, 0xbfb8aa3b, v71
	v_exp_f32_e32 v75, v75
	v_exp_f32_e32 v77, v76
	v_mul_f32_e32 v79, 0xbfb8aa3b, v68
	v_mul_f32_e32 v80, 0xbfb8aa3b, v73
	v_add_f32_e32 v75, 1.0, v75
	v_mul_f32_e32 v74, 0xbfb8aa3b, v70
	v_rcp_f32_e32 v76, v75
	v_add_f32_e32 v75, 1.0, v77
	v_mul_f32_e32 v77, 0xbfb8aa3b, v67
	v_mul_f32_e32 v78, 0xbfb8aa3b, v72
	v_exp_f32_e32 v79, v79
	v_exp_f32_e32 v81, v80
	v_mul_f32_e32 v80, 0xbfb8aa3b, v69
	v_exp_f32_e32 v74, v74
	v_exp_f32_e32 v77, v77
	v_exp_f32_e32 v78, v78
	v_exp_f32_e32 v84, v80
	v_add_f32_e32 v79, 1.0, v79
	v_add_f32_e32 v74, 1.0, v74
	v_add_f32_e32 v77, 1.0, v77
	v_add_f32_e32 v78, 1.0, v78
	v_rcp_f32_e32 v80, v79
	v_add_f32_e32 v79, 1.0, v81
	v_add_f32_e32 v81, 1.0, v84
	v_rcp_f32_e32 v74, v74
	v_rcp_f32_e32 v75, v75
	v_rcp_f32_e32 v78, v78
	v_rcp_f32_e32 v79, v79
	v_rcp_f32_e32 v81, v81
	v_rcp_f32_e32 v77, v77
	v_pk_mul_f32 v[70:71], v[70:71], v[74:75]
	v_pk_mul_f32 v[72:73], v[72:73], v[78:79]
	v_pk_mul_f32 v[68:69], v[68:69], v[80:81]
	v_pk_mul_f32 v[66:67], v[66:67], v[76:77]
; __device__ __forceinline__ unsigned cvt_pk_bf16(float lo, float hi) { unsigned r; asm volatile("v_cvt_pk_bf16_f32 %0, %1, %2" : "=v"(r) : "v"(lo), "v"(hi)); return r; }
; __device__ __forceinline__ float silu_f(float v) { return v * __builtin_amdgcn_rcpf(1.0f + __builtin_amdgcn_exp2f(-1.4426950408889634f * v)); }
;     __device__ __forceinline__ void operator()(const f32x4 (&acc)[2][2][4][2], const Unit& u, int wr, int wc, int fr, int fq) const {
;     ...
;             for (int m = 0; m < 4; ++m) { bf16_t* rowp = base + (size_t)(row0 + ai * HALF + m * 16) * ldc + col0;
; #pragma unroll
;                 for (int bj = 0; bj < 2; ++bj) { f32x4 v0 = acc[ai][bj][m][0], v1 = acc[ai][bj][m][1];
;                     if (act) {
; #pragma unroll
;                         for (int e = 0; e < 4; ++e) { v0[e] = silu_f(v0[e]); v1[e] = silu_f(v1[e]); } }
;                     u32x4 w; w.x = cvt_pk_bf16(v0[0], v0[1]); w.y = cvt_pk_bf16(v0[2], v0[3]); w.z = cvt_pk_bf16(v1[0], v1[1]); w.w = cvt_pk_bf16(v1[2], v1[3]);
;                     *(u32x4*)(rowp + bj * HALF) = w; } }
.LBB0_141:
	s_and_b64 vcc, exec, s[4:5]
	v_cvt_pk_bf16_f32 v70, v70, v71
	v_cvt_pk_bf16_f32 v71, v72, v73
	v_cvt_pk_bf16_f32 v72, v66, v67
	v_cvt_pk_bf16_f32 v73, v68, v69
	global_store_dwordx4 v[82:83], v[70:73], off offset:256 nt
	s_cbranch_vccnz .LBB0_143
	v_mul_f32_e32 v67, 0xbfb8aa3b, v58
	v_mul_f32_e32 v68, 0xbfb8aa3b, v63
	v_exp_f32_e32 v67, v67
	v_exp_f32_e32 v69, v68
	v_mul_f32_e32 v71, 0xbfb8aa3b, v60
	v_mul_f32_e32 v72, 0xbfb8aa3b, v65
	v_add_f32_e32 v67, 1.0, v67
	v_mul_f32_e32 v66, 0xbfb8aa3b, v62
	v_rcp_f32_e32 v68, v67
	v_add_f32_e32 v67, 1.0, v69
	v_mul_f32_e32 v69, 0xbfb8aa3b, v59
	v_mul_f32_e32 v70, 0xbfb8aa3b, v64
	v_exp_f32_e32 v71, v71
	v_exp_f32_e32 v73, v72
	v_mul_f32_e32 v72, 0xbfb8aa3b, v61
	v_exp_f32_e32 v66, v66
	v_exp_f32_e32 v69, v69
	v_exp_f32_e32 v70, v70
	v_exp_f32_e32 v74, v72
	v_add_f32_e32 v71, 1.0, v71
	v_add_f32_e32 v66, 1.0, v66
	v_add_f32_e32 v69, 1.0, v69
	v_add_f32_e32 v70, 1.0, v70
	v_rcp_f32_e32 v72, v71
	v_add_f32_e32 v71, 1.0, v73
	v_add_f32_e32 v73, 1.0, v74
	v_rcp_f32_e32 v66, v66
	v_rcp_f32_e32 v67, v67
	v_rcp_f32_e32 v70, v70
	v_rcp_f32_e32 v71, v71
	v_rcp_f32_e32 v73, v73
	v_rcp_f32_e32 v69, v69
	v_pk_mul_f32 v[62:63], v[62:63], v[66:67]
	v_pk_mul_f32 v[64:65], v[64:65], v[70:71]
	v_pk_mul_f32 v[60:61], v[60:61], v[72:73]
	v_pk_mul_f32 v[58:59], v[58:59], v[68:69]
.LBB0_143:
	v_add_u32_e32 v66, 0x80, v148
	v_ashrrev_i32_e32 v67, 31, v66
	v_lshlrev_b64 v[66:67], s17, v[66:67]
	v_lshl_add_u64 v[66:67], v[66:67], 1, v[150:151]
	s_and_b64 vcc, exec, s[4:5]
	v_cvt_pk_bf16_f32 v62, v62, v63
	v_cvt_pk_bf16_f32 v63, v64, v65
	v_cvt_pk_bf16_f32 v64, v58, v59
	v_cvt_pk_bf16_f32 v65, v60, v61
	global_store_dwordx4 v[66:67], v[62:65], off nt
	s_cbranch_vccnz .LBB0_145
	v_mul_f32_e32 v59, 0xbfb8aa3b, v50
	v_mul_f32_e32 v60, 0xbfb8aa3b, v55
	v_exp_f32_e32 v59, v59
	v_exp_f32_e32 v61, v60
	v_mul_f32_e32 v63, 0xbfb8aa3b, v52
	v_mul_f32_e32 v64, 0xbfb8aa3b, v57
	v_add_f32_e32 v59, 1.0, v59
	v_mul_f32_e32 v58, 0xbfb8aa3b, v54
	v_rcp_f32_e32 v60, v59
	v_add_f32_e32 v59, 1.0, v61
	v_mul_f32_e32 v61, 0xbfb8aa3b, v51
	v_mul_f32_e32 v62, 0xbfb8aa3b, v56
	v_exp_f32_e32 v63, v63
	v_exp_f32_e32 v65, v64
	v_mul_f32_e32 v64, 0xbfb8aa3b, v53
	v_exp_f32_e32 v58, v58
	v_exp_f32_e32 v61, v61
	v_exp_f32_e32 v62, v62
	v_exp_f32_e32 v68, v64
	v_add_f32_e32 v63, 1.0, v63
	v_add_f32_e32 v58, 1.0, v58
	v_add_f32_e32 v61, 1.0, v61
	v_add_f32_e32 v62, 1.0, v62
	v_rcp_f32_e32 v64, v63
	v_add_f32_e32 v63, 1.0, v65
	v_add_f32_e32 v65, 1.0, v68
	v_rcp_f32_e32 v58, v58
	v_rcp_f32_e32 v59, v59
	v_rcp_f32_e32 v62, v62
	v_rcp_f32_e32 v63, v63
	v_rcp_f32_e32 v65, v65
	v_rcp_f32_e32 v61, v61
	v_pk_mul_f32 v[54:55], v[54:55], v[58:59]
	v_pk_mul_f32 v[56:57], v[56:57], v[62:63]
	v_pk_mul_f32 v[52:53], v[52:53], v[64:65]
	v_pk_mul_f32 v[50:51], v[50:51], v[60:61]
.LBB0_145:
	s_and_b64 vcc, exec, s[4:5]
	v_cvt_pk_bf16_f32 v54, v54, v55
	v_cvt_pk_bf16_f32 v55, v56, v57
	v_cvt_pk_bf16_f32 v56, v50, v51
	v_cvt_pk_bf16_f32 v57, v52, v53
	global_store_dwordx4 v[66:67], v[54:57], off offset:256 nt
	s_cbranch_vccnz .LBB0_147
	v_mul_f32_e32 v51, 0xbfb8aa3b, v42
	v_mul_f32_e32 v52, 0xbfb8aa3b, v47
	v_exp_f32_e32 v51, v51
	v_exp_f32_e32 v53, v52
	v_mul_f32_e32 v55, 0xbfb8aa3b, v44
	v_mul_f32_e32 v56, 0xbfb8aa3b, v49
	v_add_f32_e32 v51, 1.0, v51
	v_mul_f32_e32 v50, 0xbfb8aa3b, v46
	v_rcp_f32_e32 v52, v51
	v_add_f32_e32 v51, 1.0, v53
	v_mul_f32_e32 v53, 0xbfb8aa3b, v43
	v_mul_f32_e32 v54, 0xbfb8aa3b, v48
	v_exp_f32_e32 v55, v55
	v_exp_f32_e32 v57, v56
	v_mul_f32_e32 v56, 0xbfb8aa3b, v45
	v_exp_f32_e32 v50, v50
	v_exp_f32_e32 v53, v53
	v_exp_f32_e32 v54, v54
	v_exp_f32_e32 v58, v56
	v_add_f32_e32 v55, 1.0, v55
	v_add_f32_e32 v50, 1.0, v50
	v_add_f32_e32 v53, 1.0, v53
	v_add_f32_e32 v54, 1.0, v54
	v_rcp_f32_e32 v56, v55
	v_add_f32_e32 v55, 1.0, v57
	v_add_f32_e32 v57, 1.0, v58
	v_rcp_f32_e32 v50, v50
	v_rcp_f32_e32 v51, v51
	v_rcp_f32_e32 v54, v54
	v_rcp_f32_e32 v55, v55
	v_rcp_f32_e32 v57, v57
	v_rcp_f32_e32 v53, v53
	v_pk_mul_f32 v[46:47], v[46:47], v[50:51]
	v_pk_mul_f32 v[48:49], v[48:49], v[54:55]
	v_pk_mul_f32 v[44:45], v[44:45], v[56:57]
	v_pk_mul_f32 v[42:43], v[42:43], v[52:53]
.LBB0_147:
	v_add_u32_e32 v50, 0x90, v148
	v_ashrrev_i32_e32 v51, 31, v50
	v_lshlrev_b64 v[50:51], s17, v[50:51]
	v_lshl_add_u64 v[50:51], v[50:51], 1, v[150:151]
	s_and_b64 vcc, exec, s[4:5]
	v_cvt_pk_bf16_f32 v46, v46, v47
	v_cvt_pk_bf16_f32 v47, v48, v49
	v_cvt_pk_bf16_f32 v48, v42, v43
	v_cvt_pk_bf16_f32 v49, v44, v45
	global_store_dwordx4 v[50:51], v[46:49], off nt
	s_cbranch_vccnz .LBB0_149
	v_mul_f32_e32 v43, 0xbfb8aa3b, v34
	v_mul_f32_e32 v44, 0xbfb8aa3b, v39
	v_exp_f32_e32 v43, v43
	v_exp_f32_e32 v45, v44
	v_mul_f32_e32 v47, 0xbfb8aa3b, v36
	v_mul_f32_e32 v48, 0xbfb8aa3b, v41
	v_add_f32_e32 v43, 1.0, v43
	v_mul_f32_e32 v42, 0xbfb8aa3b, v38
	v_rcp_f32_e32 v44, v43
	v_add_f32_e32 v43, 1.0, v45
	v_mul_f32_e32 v45, 0xbfb8aa3b, v35
	v_mul_f32_e32 v46, 0xbfb8aa3b, v40
	v_exp_f32_e32 v47, v47
	v_exp_f32_e32 v49, v48
	v_mul_f32_e32 v48, 0xbfb8aa3b, v37
	v_exp_f32_e32 v42, v42
	v_exp_f32_e32 v45, v45
	v_exp_f32_e32 v46, v46
	v_exp_f32_e32 v52, v48
	v_add_f32_e32 v47, 1.0, v47
	v_add_f32_e32 v42, 1.0, v42
	v_add_f32_e32 v45, 1.0, v45
	v_add_f32_e32 v46, 1.0, v46
	v_rcp_f32_e32 v48, v47
	v_add_f32_e32 v47, 1.0, v49
	v_add_f32_e32 v49, 1.0, v52
	v_rcp_f32_e32 v42, v42
	v_rcp_f32_e32 v43, v43
	v_rcp_f32_e32 v46, v46
	v_rcp_f32_e32 v47, v47
	v_rcp_f32_e32 v49, v49
	v_rcp_f32_e32 v45, v45
	v_pk_mul_f32 v[38:39], v[38:39], v[42:43]
	v_pk_mul_f32 v[40:41], v[40:41], v[46:47]
	v_pk_mul_f32 v[36:37], v[36:37], v[48:49]
	v_pk_mul_f32 v[34:35], v[34:35], v[44:45]
; __device__ __forceinline__ unsigned cvt_pk_bf16(float lo, float hi) { unsigned r; asm volatile("v_cvt_pk_bf16_f32 %0, %1, %2" : "=v"(r) : "v"(lo), "v"(hi)); return r; }
; __device__ __forceinline__ float silu_f(float v) { return v * __builtin_amdgcn_rcpf(1.0f + __builtin_amdgcn_exp2f(-1.4426950408889634f * v)); }
;     __device__ __forceinline__ void operator()(const f32x4 (&acc)[2][2][4][2], const Unit& u, int wr, int wc, int fr, int fq) const {
;     ...
;             for (int m = 0; m < 4; ++m) { bf16_t* rowp = base + (size_t)(row0 + ai * HALF + m * 16) * ldc + col0;
; #pragma unroll
;                 for (int bj = 0; bj < 2; ++bj) { f32x4 v0 = acc[ai][bj][m][0], v1 = acc[ai][bj][m][1];
;                     if (act) {
; #pragma unroll
;                         for (int e = 0; e < 4; ++e) { v0[e] = silu_f(v0[e]); v1[e] = silu_f(v1[e]); } }
;                     u32x4 w; w.x = cvt_pk_bf16(v0[0], v0[1]); w.y = cvt_pk_bf16(v0[2], v0[3]); w.z = cvt_pk_bf16(v1[0], v1[1]); w.w = cvt_pk_bf16(v1[2], v1[3]);
;                     *(u32x4*)(rowp + bj * HALF) = w; } }
.LBB0_149:
	s_and_b64 vcc, exec, s[4:5]
	v_cvt_pk_bf16_f32 v38, v38, v39
	v_cvt_pk_bf16_f32 v39, v40, v41
	v_cvt_pk_bf16_f32 v40, v34, v35
	v_cvt_pk_bf16_f32 v41, v36, v37
	global_store_dwordx4 v[50:51], v[38:41], off offset:256 nt
	s_cbranch_vccnz .LBB0_151
	v_mul_f32_e32 v35, 0xbfb8aa3b, v26
	v_mul_f32_e32 v36, 0xbfb8aa3b, v31
	v_exp_f32_e32 v35, v35
	v_exp_f32_e32 v37, v36
	v_mul_f32_e32 v39, 0xbfb8aa3b, v28
	v_mul_f32_e32 v40, 0xbfb8aa3b, v33
	v_add_f32_e32 v35, 1.0, v35
	v_mul_f32_e32 v34, 0xbfb8aa3b, v30
	v_rcp_f32_e32 v36, v35
	v_add_f32_e32 v35, 1.0, v37
	v_mul_f32_e32 v37, 0xbfb8aa3b, v27
	v_mul_f32_e32 v38, 0xbfb8aa3b, v32
	v_exp_f32_e32 v39, v39
	v_exp_f32_e32 v41, v40
	v_mul_f32_e32 v40, 0xbfb8aa3b, v29
	v_exp_f32_e32 v34, v34
	v_exp_f32_e32 v37, v37
	v_exp_f32_e32 v38, v38
	v_exp_f32_e32 v42, v40
	v_add_f32_e32 v39, 1.0, v39
	v_add_f32_e32 v34, 1.0, v34
	v_add_f32_e32 v37, 1.0, v37
	v_add_f32_e32 v38, 1.0, v38
	v_rcp_f32_e32 v40, v39
	v_add_f32_e32 v39, 1.0, v41
	v_add_f32_e32 v41, 1.0, v42
	v_rcp_f32_e32 v34, v34
	v_rcp_f32_e32 v35, v35
	v_rcp_f32_e32 v38, v38
	v_rcp_f32_e32 v39, v39
	v_rcp_f32_e32 v41, v41
	v_rcp_f32_e32 v37, v37
	v_pk_mul_f32 v[30:31], v[30:31], v[34:35]
	v_pk_mul_f32 v[32:33], v[32:33], v[38:39]
	v_pk_mul_f32 v[28:29], v[28:29], v[40:41]
	v_pk_mul_f32 v[26:27], v[26:27], v[36:37]
.LBB0_151:
	v_add_u32_e32 v34, 0xa0, v148
	v_ashrrev_i32_e32 v35, 31, v34
	v_lshlrev_b64 v[34:35], s17, v[34:35]
	v_lshl_add_u64 v[34:35], v[34:35], 1, v[150:151]
	s_and_b64 vcc, exec, s[4:5]
	v_cvt_pk_bf16_f32 v30, v30, v31
	v_cvt_pk_bf16_f32 v31, v32, v33
	v_cvt_pk_bf16_f32 v32, v26, v27
	v_cvt_pk_bf16_f32 v33, v28, v29
	global_store_dwordx4 v[34:35], v[30:33], off nt
	s_cbranch_vccnz .LBB0_153
	v_mul_f32_e32 v27, 0xbfb8aa3b, v18
	v_mul_f32_e32 v28, 0xbfb8aa3b, v23
	v_exp_f32_e32 v27, v27
	v_exp_f32_e32 v29, v28
	v_mul_f32_e32 v31, 0xbfb8aa3b, v20
	v_mul_f32_e32 v32, 0xbfb8aa3b, v25
	v_add_f32_e32 v27, 1.0, v27
	v_mul_f32_e32 v26, 0xbfb8aa3b, v22
	v_rcp_f32_e32 v28, v27
	v_add_f32_e32 v27, 1.0, v29
	v_mul_f32_e32 v29, 0xbfb8aa3b, v19
	v_mul_f32_e32 v30, 0xbfb8aa3b, v24
	v_exp_f32_e32 v31, v31
	v_exp_f32_e32 v33, v32
	v_mul_f32_e32 v32, 0xbfb8aa3b, v21
	v_exp_f32_e32 v26, v26
	v_exp_f32_e32 v29, v29
	v_exp_f32_e32 v30, v30
	v_exp_f32_e32 v36, v32
	v_add_f32_e32 v31, 1.0, v31
	v_add_f32_e32 v26, 1.0, v26
	v_add_f32_e32 v29, 1.0, v29
	v_add_f32_e32 v30, 1.0, v30
	v_rcp_f32_e32 v32, v31
	v_add_f32_e32 v31, 1.0, v33
	v_add_f32_e32 v33, 1.0, v36
	v_rcp_f32_e32 v26, v26
	v_rcp_f32_e32 v27, v27
	v_rcp_f32_e32 v30, v30
	v_rcp_f32_e32 v31, v31
	v_rcp_f32_e32 v33, v33
	v_rcp_f32_e32 v29, v29
	v_pk_mul_f32 v[22:23], v[22:23], v[26:27]
	v_pk_mul_f32 v[24:25], v[24:25], v[30:31]
	v_pk_mul_f32 v[20:21], v[20:21], v[32:33]
	v_pk_mul_f32 v[18:19], v[18:19], v[28:29]
.LBB0_153:
	s_and_b64 vcc, exec, s[4:5]
	v_cvt_pk_bf16_f32 v22, v22, v23
	v_cvt_pk_bf16_f32 v23, v24, v25
	v_cvt_pk_bf16_f32 v24, v18, v19
	v_cvt_pk_bf16_f32 v25, v20, v21
	global_store_dwordx4 v[34:35], v[22:25], off offset:256 nt
	s_cbranch_vccnz .LBB0_155
	v_mul_f32_e32 v19, 0xbfb8aa3b, v10
	v_mul_f32_e32 v20, 0xbfb8aa3b, v15
	v_exp_f32_e32 v19, v19
	v_exp_f32_e32 v21, v20
	v_mul_f32_e32 v23, 0xbfb8aa3b, v12
	v_mul_f32_e32 v24, 0xbfb8aa3b, v17
	v_add_f32_e32 v19, 1.0, v19
	v_mul_f32_e32 v18, 0xbfb8aa3b, v14
	v_rcp_f32_e32 v20, v19
	v_add_f32_e32 v19, 1.0, v21
	v_mul_f32_e32 v21, 0xbfb8aa3b, v11
	v_mul_f32_e32 v22, 0xbfb8aa3b, v16
	v_exp_f32_e32 v23, v23
	v_exp_f32_e32 v25, v24
	v_mul_f32_e32 v24, 0xbfb8aa3b, v13
	v_exp_f32_e32 v18, v18
	v_exp_f32_e32 v21, v21
	v_exp_f32_e32 v22, v22
	v_exp_f32_e32 v26, v24
	v_add_f32_e32 v23, 1.0, v23
	v_add_f32_e32 v18, 1.0, v18
	v_add_f32_e32 v21, 1.0, v21
	v_add_f32_e32 v22, 1.0, v22
	v_rcp_f32_e32 v24, v23
	v_add_f32_e32 v23, 1.0, v25
	v_add_f32_e32 v25, 1.0, v26
	v_rcp_f32_e32 v18, v18
	v_rcp_f32_e32 v19, v19
	v_rcp_f32_e32 v22, v22
	v_rcp_f32_e32 v23, v23
	v_rcp_f32_e32 v25, v25
	v_rcp_f32_e32 v21, v21
	v_pk_mul_f32 v[14:15], v[14:15], v[18:19]
	v_pk_mul_f32 v[16:17], v[16:17], v[22:23]
	v_pk_mul_f32 v[12:13], v[12:13], v[24:25]
	v_pk_mul_f32 v[10:11], v[10:11], v[20:21]
.LBB0_155:
	v_add_u32_e32 v18, 0xb0, v148
	v_ashrrev_i32_e32 v19, 31, v18
	v_lshlrev_b64 v[18:19], s17, v[18:19]
	v_lshl_add_u64 v[18:19], v[18:19], 1, v[150:151]
	s_and_b64 vcc, exec, s[4:5]
	v_cvt_pk_bf16_f32 v14, v14, v15
	v_cvt_pk_bf16_f32 v15, v16, v17
	v_cvt_pk_bf16_f32 v16, v10, v11
	v_cvt_pk_bf16_f32 v17, v12, v13
	global_store_dwordx4 v[18:19], v[14:17], off nt
	s_cbranch_vccnz .LBB0_157
	v_mul_f32_e32 v11, 0xbfb8aa3b, v2
	v_mul_f32_e32 v12, 0xbfb8aa3b, v7
	v_exp_f32_e32 v11, v11
	v_exp_f32_e32 v13, v12
	v_mul_f32_e32 v15, 0xbfb8aa3b, v4
	v_mul_f32_e32 v16, 0xbfb8aa3b, v9
	v_add_f32_e32 v11, 1.0, v11
	v_mul_f32_e32 v10, 0xbfb8aa3b, v6
	v_rcp_f32_e32 v12, v11
	v_add_f32_e32 v11, 1.0, v13
	v_mul_f32_e32 v13, 0xbfb8aa3b, v3
	v_mul_f32_e32 v14, 0xbfb8aa3b, v8
	v_exp_f32_e32 v15, v15
	v_exp_f32_e32 v17, v16
	v_mul_f32_e32 v16, 0xbfb8aa3b, v5
	v_exp_f32_e32 v10, v10
	v_exp_f32_e32 v13, v13
	v_exp_f32_e32 v14, v14
	v_exp_f32_e32 v20, v16
	v_add_f32_e32 v15, 1.0, v15
	v_add_f32_e32 v10, 1.0, v10
	v_add_f32_e32 v13, 1.0, v13
	v_add_f32_e32 v14, 1.0, v14
	v_rcp_f32_e32 v16, v15
	v_add_f32_e32 v15, 1.0, v17
	v_add_f32_e32 v17, 1.0, v20
	v_rcp_f32_e32 v10, v10
	v_rcp_f32_e32 v11, v11
	v_rcp_f32_e32 v14, v14
	v_rcp_f32_e32 v15, v15
	v_rcp_f32_e32 v17, v17
	v_rcp_f32_e32 v13, v13
	v_pk_mul_f32 v[6:7], v[6:7], v[10:11]
	v_pk_mul_f32 v[8:9], v[8:9], v[14:15]
	v_pk_mul_f32 v[4:5], v[4:5], v[16:17]
	v_pk_mul_f32 v[2:3], v[2:3], v[12:13]
.LBB0_157:
	s_andn2_b64 vcc, exec, s[6:7]
	s_mov_b64 s[4:5], -1
	v_cvt_pk_bf16_f32 v6, v6, v7
	v_cvt_pk_bf16_f32 v7, v8, v9
	v_cvt_pk_bf16_f32 v8, v2, v3
	v_cvt_pk_bf16_f32 v9, v4, v5
	global_store_dwordx4 v[18:19], v[6:9], off offset:256 nt
	s_cbranch_vccnz .LBB0_98
	s_andn2_b64 vcc, exec, s[8:9]
	s_cbranch_vccnz .LBB0_97
	s_barrier
	s_branch .LBB0_97
